# v49 + retention step start: single counted vmcnt wait for the prefetched rows (no ladder that also drains the previous step's stores/atomics)
# speedup vs baseline: 1.0060x; 1.0060x over previous
.LBB0_896:
	s_cmp_gt_u32 s49, 2
	s_cbranch_scc1 .Lret_a_latent
	s_waitcnt vmcnt(0)
	s_branch .Lret_a_done
.Lret_a_latent:
	s_and_b64 vcc, exec, s[44:45]
	s_cbranch_vccz .Lret_a_done
	s_waitcnt vmcnt(4)
.Lret_a_done:
	v_mov_b32_e32 v232, v227
	v_mov_b32_e32 v234, v193
	v_mov_b32_e32 v197, v202
	v_mov_b32_e32 v233, v201
	s_and_b64 vcc, exec, s[54:55]
	s_barrier
	s_cbranch_vccz .LBB0_898
	s_waitcnt lgkmcnt(0)
	v_mad_u64_u32 v[2:3], s[14:15], v197, s68, v[192:193]
	ds_write_b128 v2, v[156:159]
.LBB0_898:
	v_add_u32_e32 v1, 1, v197
	v_cvt_f32_i32_e32 v1, v1
	v_mul_lo_u32 v6, v197, s68
	s_waitcnt lgkmcnt(0)
	v_lshlrev_b32_e32 v2, 16, v160
	v_and_b32_e32 v3, 0xffff0000, v160
	v_mul_f32_e64 v1, -v232, v1
	v_exp_f32_e32 v1, v1
	v_add_u32_e32 v228, v192, v6
	ds_write_b128 v249, v[184:187] offset:34816
	v_and_b32_e32 v4, 0xffff0000, v161
	v_mul_f32_e32 v1, 0x3d800000, v1
	v_mul_f32_e32 v2, v1, v2
	v_mul_f32_e32 v3, v1, v3
	v_cvt_pk_bf16_f32 v2, v2, v3
	v_lshlrev_b32_e32 v3, 16, v161
	v_mul_f32_e32 v3, v1, v3
	v_mul_f32_e32 v4, v1, v4
	v_cvt_pk_bf16_f32 v3, v3, v4
	v_lshlrev_b32_e32 v4, 16, v162
	v_and_b32_e32 v5, 0xffff0000, v162
	v_mul_f32_e32 v4, v1, v4
	v_mul_f32_e32 v5, v1, v5
	v_cvt_pk_bf16_f32 v4, v4, v5
	v_lshlrev_b32_e32 v5, 16, v163
	v_and_b32_e32 v7, 0xffff0000, v163
	v_mul_f32_e32 v5, v1, v5
	v_mul_f32_e32 v1, v1, v7
	v_cvt_pk_bf16_f32 v5, v5, v1
	v_add_u32_e32 v1, 0x11000, v249
	ds_write_b128 v1, v[2:5]
	v_cndmask_b32_e64 v2, 0, 1, s[54:55]
	v_cmp_ne_u32_e64 s[16:17], 1, v2
	s_andn2_b64 vcc, exec, s[54:55]
	v_add_u32_e32 v231, 32, v197
	s_cbranch_vccnz .LBB0_900
	v_mad_u64_u32 v[2:3], s[14:15], v231, s68, v[192:193]
	ds_write_b128 v2, v[152:155]
.LBB0_900:
	v_add_u32_e32 v2, 33, v197
	v_cvt_f32_i32_e32 v2, v2
	v_lshlrev_b32_e32 v3, 16, v164
	v_and_b32_e32 v4, 0xffff0000, v164
	ds_write_b128 v249, v[188:191] offset:43008
	v_mul_f32_e64 v2, -v232, v2
	v_exp_f32_e32 v2, v2
	v_lshlrev_b32_e32 v5, 16, v165
	v_and_b32_e32 v7, 0xffff0000, v167
	s_and_b64 vcc, exec, s[16:17]
	v_mul_f32_e32 v6, 0x3d800000, v2
	v_mul_f32_e32 v2, v6, v3
	v_mul_f32_e32 v3, v6, v4
	v_cvt_pk_bf16_f32 v2, v2, v3
	v_and_b32_e32 v3, 0xffff0000, v165
	v_mul_f32_e32 v4, v6, v5
	v_mul_f32_e32 v3, v6, v3
	v_cvt_pk_bf16_f32 v3, v4, v3
	v_lshlrev_b32_e32 v4, 16, v166
	v_and_b32_e32 v5, 0xffff0000, v166
	v_mul_f32_e32 v4, v6, v4
	v_mul_f32_e32 v5, v6, v5
	v_cvt_pk_bf16_f32 v4, v4, v5
	v_lshlrev_b32_e32 v5, 16, v167
	v_mul_f32_e32 v5, v6, v5
	v_add_u32_e32 v230, 64, v197
	v_mul_f32_e32 v6, v6, v7
	v_cvt_pk_bf16_f32 v5, v5, v6
	ds_write_b128 v1, v[2:5] offset:8192
	s_cbranch_vccnz .LBB0_902
	v_mad_u64_u32 v[2:3], s[14:15], v230, s68, v[192:193]
	ds_write_b128 v2, v[148:151]
.LBB0_902:
	v_add_u32_e32 v2, 0x41, v197
	v_cvt_f32_i32_e32 v2, v2
	v_lshlrev_b32_e32 v3, 16, v168
	v_and_b32_e32 v4, 0xffff0000, v168
	ds_write_b128 v249, v[180:183] offset:51200
	v_mul_f32_e64 v2, -v232, v2
	v_exp_f32_e32 v2, v2
	v_lshlrev_b32_e32 v5, 16, v169
	v_and_b32_e32 v7, 0xffff0000, v171
	s_and_b64 vcc, exec, s[16:17]
	v_mul_f32_e32 v6, 0x3d800000, v2
	v_mul_f32_e32 v2, v6, v3
	v_mul_f32_e32 v3, v6, v4
	v_cvt_pk_bf16_f32 v2, v2, v3
	v_and_b32_e32 v3, 0xffff0000, v169
	v_mul_f32_e32 v4, v6, v5
	v_mul_f32_e32 v3, v6, v3
	v_cvt_pk_bf16_f32 v3, v4, v3
	v_lshlrev_b32_e32 v4, 16, v170
	v_and_b32_e32 v5, 0xffff0000, v170
	v_mul_f32_e32 v4, v6, v4
	v_mul_f32_e32 v5, v6, v5
	v_cvt_pk_bf16_f32 v4, v4, v5
	v_lshlrev_b32_e32 v5, 16, v171
	v_mul_f32_e32 v5, v6, v5
	v_add_u32_e32 v229, 0x60, v197
	v_mul_f32_e32 v6, v6, v7
	v_cvt_pk_bf16_f32 v5, v5, v6
	ds_write_b128 v1, v[2:5] offset:16384
	s_cbranch_vccnz .LBB0_904
	v_mad_u64_u32 v[2:3], s[14:15], v229, s68, v[192:193]
	ds_write_b128 v2, v[144:147]
.LBB0_904:
	v_add_u32_e32 v2, 0x61, v197
	v_cvt_f32_i32_e32 v2, v2
	v_lshlrev_b32_e32 v3, 16, v172
	v_and_b32_e32 v4, 0xffff0000, v172
	ds_write_b128 v249, v[176:179] offset:59392
	v_mul_f32_e64 v2, -v232, v2
	v_exp_f32_e32 v2, v2
	v_lshlrev_b32_e32 v5, 16, v173
	v_and_b32_e32 v7, 0xffff0000, v175
	s_and_b64 vcc, exec, s[54:55]
	v_mul_f32_e32 v6, 0x3d800000, v2
	v_mul_f32_e32 v2, v6, v3
	v_mul_f32_e32 v3, v6, v4
	v_cvt_pk_bf16_f32 v2, v2, v3
	v_and_b32_e32 v3, 0xffff0000, v173
	v_mul_f32_e32 v4, v6, v5
	v_mul_f32_e32 v3, v6, v3
	v_cvt_pk_bf16_f32 v3, v4, v3
	v_lshlrev_b32_e32 v4, 16, v174
	v_and_b32_e32 v5, 0xffff0000, v174
	v_mul_f32_e32 v4, v6, v4
	v_mul_f32_e32 v5, v6, v5
	v_cvt_pk_bf16_f32 v4, v4, v5
	v_lshlrev_b32_e32 v5, 16, v175
	v_mul_f32_e32 v5, v6, v5
	s_mov_b64 s[14:15], s[30:31]
	v_mul_f32_e32 v6, v6, v7
	v_cvt_pk_bf16_f32 v5, v5, v6
	ds_write_b128 v1, v[2:5] offset:24576
	s_cbranch_vccz .LBB0_906
	v_cvt_pk_bf16_f32 v2, v64, v65
	v_cvt_pk_bf16_f32 v3, v66, v67
	ds_write_b64 v225, v[2:3]
	v_cvt_pk_bf16_f32 v2, v68, v69
	v_cvt_pk_bf16_f32 v3, v70, v71
	ds_write_b64 v225, v[2:3] offset:16
	v_cvt_pk_bf16_f32 v2, v72, v73
	v_cvt_pk_bf16_f32 v3, v74, v75
	ds_write_b64 v225, v[2:3] offset:32
	v_cvt_pk_bf16_f32 v2, v76, v77
	v_cvt_pk_bf16_f32 v3, v78, v79
	ds_write_b64 v225, v[2:3] offset:48
	v_cvt_pk_bf16_f32 v2, v48, v49
	v_cvt_pk_bf16_f32 v3, v50, v51
	ds_write_b64 v225, v[2:3] offset:64
	v_cvt_pk_bf16_f32 v2, v52, v53
	v_cvt_pk_bf16_f32 v3, v54, v55
	ds_write_b64 v225, v[2:3] offset:80
	v_cvt_pk_bf16_f32 v2, v56, v57
	v_cvt_pk_bf16_f32 v3, v58, v59
	s_mov_b64 s[14:15], s[40:41]
	ds_write_b64 v225, v[2:3] offset:96
	v_cvt_pk_bf16_f32 v2, v60, v61
	v_cvt_pk_bf16_f32 v3, v62, v63
	ds_write_b64 v225, v[2:3] offset:112
